# hand-written ffn_fix item loop: coalesced dwordx4 loads, wave-uniform scalar addressing (was scalarized dword loads)
# speedup vs baseline: 1.6746x; 1.6746x over previous
; __device__ __forceinline__ int tidx() { int t = threadIdx.x; OPAQUE_V(t); return t; }
; __device__ __forceinline__ int bidx() { int b = blockIdx.x; OPAQUE_S(b); return b; }
; __device__ __forceinline__ float siluf(float x) { return x * __builtin_amdgcn_rcpf(1.f + __expf(-x)); }
; __device__ __forceinline__ u32x4 pack8(const float* f) { u32x4 o; o.x = pk2(f[0], f[1]); o.y = pk2(f[2], f[3]); o.z = pk2(f[4], f[5]); o.w = pk2(f[6], f[7]); return o; }
; __device__ __forceinline__ void ffn_fix_phase(const Args& a, int layer) {
;     bf16_t* U = (bf16_t*)(a.ws + BF_U); const float* GD = (const float*)(a.ws + BF_GD); const float* UD = (const float*)(a.ws + BF_UD);
;     const float* cw = a.in[33] + (size_t)layer * 3 * DFF; const float* cb = a.in[34] + (size_t)layer * DFF;
;     const size_t gt = (size_t)bidx() * NTHREADS + tidx(), NGT = (size_t)gridDim.x * NTHREADS;
;     constexpr int CPR = DFF / 8, NG = MT / 32;
;     auto fix_item = [&](size_t i, size_t& uoff) -> u32x4 {
;         const int grp = (int)(i / (2 * CPR)), s = (int)((i / CPR) & 1), c0 = (int)(i % CPR) * 8;
;         const int row = grp * 32 + s; const bool samp = row >= NTP; const bool first = samp || (grp & 63) == 0;
;         const float* hp = a.in[10] + (size_t)(layer * 16 + (samp ? grp - NTP / 32 : 0)) * 2 * DFF + c0;
;         const float* gc = GD + ((size_t)grp * 4 + 2 + s) * DFF + c0;
;         const float* g1p = s == 1 ? GD + ((size_t)grp * 4 + 2) * DFF + c0 : (first ? hp + DFF : GD + ((size_t)(grp - 1) * 4 + 1) * DFF + c0);
;         const float* g2p = s == 1 ? (first ? hp + DFF : GD + ((size_t)(grp - 1) * 4 + 1) * DFF + c0) : (first ? hp : GD + ((size_t)(grp - 1) * 4 + 0) * DFF + c0);
;         const bool z1 = (s == 0) && first && !samp, z2 = first && !samp;
;         const float* up = UD + ((size_t)grp * 2 + s) * DFF + c0;
;         float o[8];
; #pragma unroll
;         for (int k = 0; k < 8; ++k) { const float g1 = z1 ? 0.f : g1p[k], g2 = z2 ? 0.f : g2p[k];
;             const float y = cw[c0 + k] * g2 + cw[DFF + c0 + k] * g1 + cw[2 * DFF + c0 + k] * gc[k] + cb[c0 + k]; o[k] = siluf(y) * up[k]; }
;         uoff = (size_t)row * DFF + c0;
;         return pack8(o);
;     };
;     const size_t NIT = (size_t)NG * 2 * CPR;
;     for (size_t i0 = gt; i0 < NIT; i0 += 2 * NGT) {
.LBB0_2898:
	s_or_b64 exec, exec, s[0:1]
	s_mov_b32 s0, s69
	s_waitcnt lgkmcnt(0)
	s_barrier
	s_ashr_i32 s1, s0, 31
	v_mov_b32_e32 v2, v187
	s_lshl_b64 s[0:1], s[0:1], 9
	s_nop 0
	v_ashrrev_i32_e32 v3, 31, v2
	v_lshl_add_u64 v[10:11], s[0:1], 0, v[2:3]
	s_mov_b64 s[10:11], exec
	v_lshrrev_b32_e32 v3, 6, v187
	v_and_b32_e32 v4, 63, v187
	s_lshl_b32 s1, s69, 3
	v_readfirstlane_b32 s0, v3
	s_add_i32 s0, s0, s1
	s_mul_i32 s1, s0, 0x1746
	s_lshr_b32 s44, s1, 16
	s_mul_i32 s1, s44, 11
	s_sub_i32 s1, s0, s1
	s_cmp_ge_u32 s44, 0xba
	s_cbranch_scc1 .Lfix_done
	s_lshl_b32 s2, s1, 10
	v_lshl_add_u32 v0, v4, 4, s2
	s_lshl_b32 s2, s1, 9
	v_lshl_add_u32 v2, v4, 3, s2
	v_readlane_b32 s36, v253, 46
	v_readlane_b32 s37, v253, 47
	v_readlane_b32 s38, v253, 48
	v_readlane_b32 s39, v253, 49
	v_readlane_b32 s40, v253, 9
	v_readlane_b32 s41, v253, 10
	v_readlane_b32 s42, v251, 26
	v_readlane_b32 s43, v251, 27
	v_readlane_b32 s2, v254, 51
	s_mul_i32 s2, s2, 0x58000
	s_add_u32 s42, s42, s2
	s_addc_u32 s43, s43, 0
	s_add_u32 s2, s6, 0x2c00
	s_addc_u32 s3, s7, 0
	s_add_u32 s4, s6, 0x5800
	s_addc_u32 s5, s7, 0
	global_load_dwordx4 v[12:15], v0, s[6:7]
	global_load_dwordx4 v[16:19], v0, s[2:3]
	global_load_dwordx4 v[20:23], v0, s[4:5]
	global_load_dwordx4 v[24:27], v0, s[8:9]
	s_mov_b32 s45, 0
; __device__ __forceinline__ float siluf(float x) { return x * __builtin_amdgcn_rcpf(1.f + __expf(-x)); }
; __device__ __forceinline__ u32x4 pack8(const float* f) { u32x4 o; o.x = pk2(f[0], f[1]); o.y = pk2(f[2], f[3]); o.z = pk2(f[4], f[5]); o.w = pk2(f[6], f[7]); return o; }
; __device__ __forceinline__ void ffn_fix_phase(const Args& a, int layer) {
;     ...
;     auto fix_item = [&](size_t i, size_t& uoff) -> u32x4 {
;         const int grp = (int)(i / (2 * CPR)), s = (int)((i / CPR) & 1), c0 = (int)(i % CPR) * 8;
;         const int row = grp * 32 + s; const bool samp = row >= NTP; const bool first = samp || (grp & 63) == 0;
;         const float* hp = a.in[10] + (size_t)(layer * 16 + (samp ? grp - NTP / 32 : 0)) * 2 * DFF + c0;
;         const float* gc = GD + ((size_t)grp * 4 + 2 + s) * DFF + c0;
;         const float* g1p = s == 1 ? GD + ((size_t)grp * 4 + 2) * DFF + c0 : (first ? hp + DFF : GD + ((size_t)(grp - 1) * 4 + 1) * DFF + c0);
;         const float* g2p = s == 1 ? (first ? hp + DFF : GD + ((size_t)(grp - 1) * 4 + 1) * DFF + c0) : (first ? hp : GD + ((size_t)(grp - 1) * 4 + 0) * DFF + c0);
;         const bool z1 = (s == 0) && first && !samp, z2 = first && !samp;
;         const float* up = UD + ((size_t)grp * 2 + s) * DFF + c0;
;         float o[8];
; #pragma unroll
;         for (int k = 0; k < 8; ++k) { const float g1 = z1 ? 0.f : g1p[k], g2 = z2 ? 0.f : g2p[k];
;             const float y = cw[c0 + k] * g2 + cw[DFF + c0 + k] * g1 + cw[2 * DFF + c0 + k] * gc[k] + cb[c0 + k]; o[k] = siluf(y) * up[k]; }
;         uoff = (size_t)row * DFF + c0;
;         return pack8(o);
;     };
;     const size_t NIT = (size_t)NG * 2 * CPR;
;     for (size_t i0 = gt; i0 < NIT; i0 += 2 * NGT) {
;         const size_t i1 = i0 + NGT; size_t u0 = 0, u1 = 0;
;         const u32x4 r0 = fix_item(i0, u0);
;         u32x4 r1 = (u32x4){0u, 0u, 0u, 0u};
;         if (i1 < NIT) r1 = fix_item(i1, u1);
;         *(u32x4*)(U + u0) = r0;
;         if (i1 < NIT) *(u32x4*)(U + u1) = r1;
;     }
.Lfix_loop:
	s_min_u32 s0, s44, 0x101f
	s_lshr_b32 s1, s0, 1
	s_and_b32 s0, s0, 1
	s_mul_i32 s12, s1, 0xb000
	s_add_u32 s16, s36, s12
	s_addc_u32 s17, s37, 0
	s_mul_i32 s13, s0, 0x2c00
	s_add_u32 s12, s16, s13
	s_addc_u32 s13, s17, 0
	s_add_u32 s12, s12, 0x5800
	s_addc_u32 s13, s13, 0
	global_load_dwordx4 v[28:31], v0, s[12:13]
	s_mul_i32 s14, s1, 0x5800
	s_mul_i32 s15, s0, 0x2c00
	s_add_u32 s14, s14, s15
	s_add_u32 s14, s38, s14
	s_addc_u32 s15, s39, 0
	global_load_dwordx4 v[40:43], v0, s[14:15]
	s_mul_i32 s12, s1, 0x2c000
	s_mul_i32 s13, s0, 0x1600
	s_add_u32 s12, s12, s13
	s_add_u32 s46, s40, s12
	s_addc_u32 s47, s41, 0
	s_sub_u32 s18, s16, 0xb000
	s_subb_u32 s19, s17, 0
	s_sub_i32 s12, s1, 0x800
	s_mul_i32 s12, s12, 0x5800
	s_add_u32 s20, s42, s12
	s_addc_u32 s21, s43, 0
	s_cmp_ge_u32 s1, 0x800
	s_cselect_b32 s12, 1, 0
	s_cselect_b32 s22, s20, s16
	s_cselect_b32 s23, s21, s17
	s_and_b32 s13, s1, 63
	s_cmp_eq_u32 s13, 0
	s_cselect_b32 s13, 1, 0
	s_or_b32 s13, s13, s12
	s_andn2_b32 s12, s13, s12
	s_cmp_lg_u32 s13, 0
	s_cselect_b32 s22, s22, s18
	s_cselect_b32 s23, s23, s19
	s_add_u32 s24, s22, 0x2c00
	s_addc_u32 s25, s23, 0
	s_add_u32 s18, s16, 0x5800
	s_addc_u32 s19, s17, 0
	s_cmp_lg_u32 s0, 0
	s_cselect_b32 s20, s18, s24
	s_cselect_b32 s21, s19, s25
	s_cselect_b32 s22, s24, s22
	s_cselect_b32 s23, s25, s23
	s_cselect_b32 s13, 0, s12
	global_load_dwordx4 v[32:35], v0, s[20:21]
	global_load_dwordx4 v[36:39], v0, s[22:23]
	s_cmp_lg_u32 s13, 0
	s_cselect_b64 s[48:49], -1, 0
	s_cmp_lg_u32 s12, 0
	s_cselect_b64 s[50:51], -1, 0
	s_add_u32 s2, s44, 0xba
	s_min_u32 s0, s2, 0x101f
	s_lshr_b32 s1, s0, 1
	s_and_b32 s0, s0, 1
	s_mul_i32 s12, s1, 0xb000
	s_add_u32 s16, s36, s12
	s_addc_u32 s17, s37, 0
	s_mul_i32 s13, s0, 0x2c00
	s_add_u32 s12, s16, s13
	s_addc_u32 s13, s17, 0
	s_add_u32 s12, s12, 0x5800
	s_addc_u32 s13, s13, 0
	global_load_dwordx4 v[44:47], v0, s[12:13]
	s_mul_i32 s14, s1, 0x5800
	s_mul_i32 s15, s0, 0x2c00
	s_add_u32 s14, s14, s15
	s_add_u32 s14, s38, s14
	s_addc_u32 s15, s39, 0
	global_load_dwordx4 v[56:59], v0, s[14:15]
	s_mul_i32 s12, s1, 0x2c000
	s_mul_i32 s13, s0, 0x1600
	s_add_u32 s12, s12, s13
	s_add_u32 s4, s40, s12
	s_addc_u32 s5, s41, 0
	s_sub_u32 s18, s16, 0xb000
	s_subb_u32 s19, s17, 0
	s_sub_i32 s12, s1, 0x800
	s_mul_i32 s12, s12, 0x5800
	s_add_u32 s20, s42, s12
	s_addc_u32 s21, s43, 0
	s_cmp_ge_u32 s1, 0x800
	s_cselect_b32 s12, 1, 0
	s_cselect_b32 s22, s20, s16
	s_cselect_b32 s23, s21, s17
	s_and_b32 s13, s1, 63
	s_cmp_eq_u32 s13, 0
	s_cselect_b32 s13, 1, 0
	s_or_b32 s13, s13, s12
	s_andn2_b32 s12, s13, s12
	s_cmp_lg_u32 s13, 0
	s_cselect_b32 s22, s22, s18
	s_cselect_b32 s23, s23, s19
	s_add_u32 s24, s22, 0x2c00
	s_addc_u32 s25, s23, 0
	s_add_u32 s18, s16, 0x5800
	s_addc_u32 s19, s17, 0
	s_cmp_lg_u32 s0, 0
	s_cselect_b32 s20, s18, s24
	s_cselect_b32 s21, s19, s25
	s_cselect_b32 s22, s24, s22
	s_cselect_b32 s23, s25, s23
	s_cselect_b32 s13, 0, s12
	global_load_dwordx4 v[48:51], v0, s[20:21]
	global_load_dwordx4 v[52:55], v0, s[22:23]
	s_cmp_lg_u32 s13, 0
	s_cselect_b64 s[2:3], -1, 0
	s_cmp_lg_u32 s12, 0
	s_cselect_b64 vcc, -1, 0
	s_waitcnt vmcnt(4)
	v_cndmask_b32_e64 v32, v32, 0, s[48:49]
	v_cndmask_b32_e64 v33, v33, 0, s[48:49]
	v_cndmask_b32_e64 v34, v34, 0, s[48:49]
	v_cndmask_b32_e64 v35, v35, 0, s[48:49]
	v_cndmask_b32_e64 v36, v36, 0, s[50:51]
	v_cndmask_b32_e64 v37, v37, 0, s[50:51]
	v_cndmask_b32_e64 v38, v38, 0, s[50:51]
	v_cndmask_b32_e64 v39, v39, 0, s[50:51]
	v_pk_mul_f32 v[60:61], v[12:13], v[36:37]
	v_pk_mul_f32 v[62:63], v[14:15], v[38:39]
	v_pk_fma_f32 v[60:61], v[16:17], v[32:33], v[60:61]
	v_pk_fma_f32 v[62:63], v[18:19], v[34:35], v[62:63]
	v_pk_fma_f32 v[60:61], v[20:21], v[28:29], v[60:61]
	v_pk_fma_f32 v[62:63], v[22:23], v[30:31], v[62:63]
	v_pk_add_f32 v[60:61], v[24:25], v[60:61]
	v_pk_add_f32 v[62:63], v[26:27], v[62:63]
	v_mul_f32_e32 v64, 0xbfb8aa3b, v60
	v_mul_f32_e32 v65, 0xbfb8aa3b, v61
	v_mul_f32_e32 v66, 0xbfb8aa3b, v62
	v_mul_f32_e32 v67, 0xbfb8aa3b, v63
	v_exp_f32_e32 v64, v64
	v_exp_f32_e32 v65, v65
	v_exp_f32_e32 v66, v66
	v_exp_f32_e32 v67, v67
	v_add_f32_e32 v64, 1.0, v64
	v_add_f32_e32 v65, 1.0, v65
	v_add_f32_e32 v66, 1.0, v66
	v_add_f32_e32 v67, 1.0, v67
	v_rcp_f32_e32 v64, v64
	v_rcp_f32_e32 v65, v65
	v_rcp_f32_e32 v66, v66
	v_rcp_f32_e32 v67, v67
	s_nop 0
	v_pk_mul_f32 v[60:61], v[60:61], v[64:65]
	v_pk_mul_f32 v[62:63], v[62:63], v[66:67]
	v_pk_mul_f32 v[60:61], v[40:41], v[60:61]
	v_pk_mul_f32 v[62:63], v[42:43], v[62:63]
	v_cvt_pk_bf16_f32 v64, v60, v61
	v_cvt_pk_bf16_f32 v65, v62, v63
	global_store_dwordx2 v2, v[64:65], s[46:47]
	s_waitcnt vmcnt(1)
	v_cndmask_b32_e64 v48, v48, 0, s[2:3]
	v_cndmask_b32_e64 v49, v49, 0, s[2:3]
	v_cndmask_b32_e64 v50, v50, 0, s[2:3]
	v_cndmask_b32_e64 v51, v51, 0, s[2:3]
	v_cndmask_b32_e64 v52, v52, 0, vcc
	v_cndmask_b32_e64 v53, v53, 0, vcc
	v_cndmask_b32_e64 v54, v54, 0, vcc
	v_cndmask_b32_e64 v55, v55, 0, vcc
	v_pk_mul_f32 v[68:69], v[12:13], v[52:53]
	v_pk_mul_f32 v[70:71], v[14:15], v[54:55]
	v_pk_fma_f32 v[68:69], v[16:17], v[48:49], v[68:69]
	v_pk_fma_f32 v[70:71], v[18:19], v[50:51], v[70:71]
	v_pk_fma_f32 v[68:69], v[20:21], v[44:45], v[68:69]
	v_pk_fma_f32 v[70:71], v[22:23], v[46:47], v[70:71]
	v_pk_add_f32 v[68:69], v[24:25], v[68:69]
	v_pk_add_f32 v[70:71], v[26:27], v[70:71]
	v_mul_f32_e32 v72, 0xbfb8aa3b, v68
	v_mul_f32_e32 v73, 0xbfb8aa3b, v69
	v_mul_f32_e32 v74, 0xbfb8aa3b, v70
	v_mul_f32_e32 v75, 0xbfb8aa3b, v71
	v_exp_f32_e32 v72, v72
	v_exp_f32_e32 v73, v73
	v_exp_f32_e32 v74, v74
	v_exp_f32_e32 v75, v75
	v_add_f32_e32 v72, 1.0, v72
	v_add_f32_e32 v73, 1.0, v73
	v_add_f32_e32 v74, 1.0, v74
	v_add_f32_e32 v75, 1.0, v75
	v_rcp_f32_e32 v72, v72
	v_rcp_f32_e32 v73, v73
	v_rcp_f32_e32 v74, v74
	v_rcp_f32_e32 v75, v75
	s_nop 0
	v_pk_mul_f32 v[68:69], v[68:69], v[72:73]
	v_pk_mul_f32 v[70:71], v[70:71], v[74:75]
	v_pk_mul_f32 v[68:69], v[56:57], v[68:69]
	v_pk_mul_f32 v[70:71], v[58:59], v[70:71]
	v_cvt_pk_bf16_f32 v72, v68, v69
	v_cvt_pk_bf16_f32 v73, v70, v71
	global_store_dwordx2 v2, v[72:73], s[4:5]
	s_add_u32 s44, s44, 0x174
	s_add_u32 s45, s45, 1
	s_cmp_lt_u32 s45, 12
	s_cbranch_scc1 .Lfix_loop
.Lfix_done:
.LBB0_3003:
	s_or_b64 exec, exec, s[10:11]
	s_mov_b64 s[0:1], 0x42000
	v_cmp_gt_u64_e32 vcc, s[0:1], v[10:11]
	s_and_saveexec_b64 s[0:1], vcc
	s_cbranch_execz .LBB0_3010
	v_readlane_b32 s3, v254, 51
	s_lshl_b32 s2, s3, 4
	s_sub_i32 s6, s2, 32
	s_lshl_b32 s7, s3, 5
	s_mov_b64 s[2:3], 0
	s_branch .LBB0_3006
